# retention cross-chunk state loads: 16 float4 loads in flight with counted vmcnt instead of 4 batches of 4
# baseline (speedup 1.0000x reference)
.LBB0_1184:
	s_and_b64 s[0:1], s[16:17], exec
	s_cselect_b32 s18, s13, s15
	s_add_i32 s18, s18, s25
	s_cmp_lt_u32 s18, 8
	s_cselect_b64 s[0:1], -1, 0
	s_cmp_gt_u32 s18, 7
	s_cbranch_scc1 .LBB0_1186
	s_or_b32 s18, s18, s26
	s_ashr_i32 s19, s18, 31
	s_lshl_b64 s[18:19], s[18:19], 22
	v_lshl_add_u64 v[2:3], v[80:81], 0, s[18:19]
	global_load_dwordx4 v[4:7], v[2:3], off
	global_load_dwordx4 v[8:11], v[2:3], off offset:16
	global_load_dwordx4 v[12:15], v[2:3], off offset:32
	global_load_dwordx4 v[84:87], v[2:3], off offset:48
	global_load_dwordx4 v[88:91], v[2:3], off offset:64
	global_load_dwordx4 v[92:95], v[2:3], off offset:80
	global_load_dwordx4 v[96:99], v[2:3], off offset:96
	global_load_dwordx4 v[100:103], v[2:3], off offset:112
	global_load_dwordx4 v[104:107], v[2:3], off offset:128
	global_load_dwordx4 v[108:111], v[2:3], off offset:144
	global_load_dwordx4 v[112:115], v[2:3], off offset:160
	global_load_dwordx4 v[116:119], v[2:3], off offset:176
	global_load_dwordx4 v[120:123], v[2:3], off offset:192
	global_load_dwordx4 v[124:127], v[2:3], off offset:208
	global_load_dwordx4 v[128:131], v[2:3], off offset:224
	global_load_dwordx4 v[132:135], v[2:3], off offset:240
	s_waitcnt vmcnt(15)
	v_pk_fma_f32 v[64:65], v[82:83], v[4:5], v[64:65] op_sel_hi:[0,1,1]
	v_pk_fma_f32 v[66:67], v[82:83], v[6:7], v[66:67] op_sel_hi:[0,1,1]
	s_waitcnt vmcnt(14)
	v_pk_fma_f32 v[68:69], v[82:83], v[8:9], v[68:69] op_sel_hi:[0,1,1]
	v_pk_fma_f32 v[70:71], v[82:83], v[10:11], v[70:71] op_sel_hi:[0,1,1]
	s_waitcnt vmcnt(13)
	v_pk_fma_f32 v[72:73], v[82:83], v[12:13], v[72:73] op_sel_hi:[0,1,1]
	v_pk_fma_f32 v[74:75], v[82:83], v[14:15], v[74:75] op_sel_hi:[0,1,1]
	s_waitcnt vmcnt(12)
	v_pk_fma_f32 v[76:77], v[82:83], v[84:85], v[76:77] op_sel_hi:[0,1,1]
	v_pk_fma_f32 v[78:79], v[82:83], v[86:87], v[78:79] op_sel_hi:[0,1,1]
	s_waitcnt vmcnt(11)
	v_pk_fma_f32 v[48:49], v[82:83], v[88:89], v[48:49] op_sel_hi:[0,1,1]
	v_pk_fma_f32 v[50:51], v[82:83], v[90:91], v[50:51] op_sel_hi:[0,1,1]
	s_waitcnt vmcnt(10)
	v_pk_fma_f32 v[52:53], v[82:83], v[92:93], v[52:53] op_sel_hi:[0,1,1]
	v_pk_fma_f32 v[54:55], v[82:83], v[94:95], v[54:55] op_sel_hi:[0,1,1]
	s_waitcnt vmcnt(9)
	v_pk_fma_f32 v[56:57], v[82:83], v[96:97], v[56:57] op_sel_hi:[0,1,1]
	v_pk_fma_f32 v[58:59], v[82:83], v[98:99], v[58:59] op_sel_hi:[0,1,1]
	s_waitcnt vmcnt(8)
	v_pk_fma_f32 v[60:61], v[82:83], v[100:101], v[60:61] op_sel_hi:[0,1,1]
	v_pk_fma_f32 v[62:63], v[82:83], v[102:103], v[62:63] op_sel_hi:[0,1,1]
	s_waitcnt vmcnt(7)
	v_pk_fma_f32 v[32:33], v[82:83], v[104:105], v[32:33] op_sel_hi:[0,1,1]
	v_pk_fma_f32 v[34:35], v[82:83], v[106:107], v[34:35] op_sel_hi:[0,1,1]
	s_waitcnt vmcnt(6)
	v_pk_fma_f32 v[36:37], v[82:83], v[108:109], v[36:37] op_sel_hi:[0,1,1]
	v_pk_fma_f32 v[38:39], v[82:83], v[110:111], v[38:39] op_sel_hi:[0,1,1]
	s_waitcnt vmcnt(5)
	v_pk_fma_f32 v[40:41], v[82:83], v[112:113], v[40:41] op_sel_hi:[0,1,1]
	v_pk_fma_f32 v[42:43], v[82:83], v[114:115], v[42:43] op_sel_hi:[0,1,1]
	s_waitcnt vmcnt(4)
	v_pk_fma_f32 v[44:45], v[82:83], v[116:117], v[44:45] op_sel_hi:[0,1,1]
	v_pk_fma_f32 v[46:47], v[82:83], v[118:119], v[46:47] op_sel_hi:[0,1,1]
	s_waitcnt vmcnt(3)
	v_pk_fma_f32 v[16:17], v[82:83], v[120:121], v[16:17] op_sel_hi:[0,1,1]
	v_pk_fma_f32 v[18:19], v[82:83], v[122:123], v[18:19] op_sel_hi:[0,1,1]
	s_waitcnt vmcnt(2)
	v_pk_fma_f32 v[20:21], v[82:83], v[124:125], v[20:21] op_sel_hi:[0,1,1]
	v_pk_fma_f32 v[22:23], v[82:83], v[126:127], v[22:23] op_sel_hi:[0,1,1]
	s_waitcnt vmcnt(1)
	v_pk_fma_f32 v[24:25], v[82:83], v[128:129], v[24:25] op_sel_hi:[0,1,1]
	v_pk_fma_f32 v[26:27], v[82:83], v[130:131], v[26:27] op_sel_hi:[0,1,1]
	s_waitcnt vmcnt(0)
	v_pk_fma_f32 v[28:29], v[82:83], v[132:133], v[28:29] op_sel_hi:[0,1,1]
	v_pk_fma_f32 v[30:31], v[82:83], v[134:135], v[30:31] op_sel_hi:[0,1,1]
	v_mul_f32_e32 v82, v83, v82
